# skip final grid barrier after last layer LN2
# speedup vs baseline: 1.0083x; 1.0083x over previous
.LBB0_1211:
	s_or_b64 exec, exec, s[8:9]
	v_readlane_b32 s0, v254, 55
	v_readlane_b32 s1, v254, 56
	s_and_b64 vcc, exec, s[0:1]
	s_cbranch_vccnz .LBB0_1256
	s_mov_b32 s0, s91
	s_mov_b32 s64, 0
	s_waitcnt vmcnt(0)
	s_waitcnt lgkmcnt(0)
	v_or_b32_e32 v0, s0, v230
	v_cmp_eq_u32_e32 vcc, 0, v0
	s_barrier
	s_and_saveexec_b64 s[0:1], vcc
	s_cbranch_execnz .LBB0_1212
	s_getpc_b64 s[98:99]
